# v095 + P1 K-loop load segments: fragment ds_reads in groups of 4 with the address math and stage loads spread between the groups
# speedup vs baseline: 1.0035x; 1.0035x over previous
; #define PG8_LAS __attribute__((address_space(3)))
; #define PG8_STAGE(bufoff, gbase, voff) do { _Pragma("unroll") for (int _i = 0; _i < 2; ++_i) \
;         __builtin_amdgcn_global_load_lds((const unsigned*)((const char*)(gbase) + (voff)[_i]), (PG8_LAS unsigned*)(lds + (bufoff) + ldsw + _i * 8192), 16, 0, 0); } while (0)
; #define PG8_WAIT_V(n) asm volatile("s_waitcnt vmcnt(" #n ")" ::: "memory")
; #define PG8_BAR __builtin_amdgcn_s_barrier()
; template <class Epi, class Sched, bool ALIGN_EPI = false, bool SP2 = false, bool RS = false, bool BPRE = false>
; __device__ __forceinline__ void gemm_phase(PG8_LAS unsigned char* lds, const Gemm g, const Sched& S, const Epi& E, const float* rs_ss = nullptr, PG8_LAS float* rs_tab = nullptr) {
;     ...
;         const bool has_next = S.next(ui + 1, nxt);
;         const char* nA = has_next ? (const char*)g.A + (size_t)nxt.pm * tstep : cA; const char* nB = has_next ? (const char*)g.Bt + (size_t)nxt.pn * tstep : cB;
;         for (int t = 0; t < nt; t += 2) {
;             const bool last = (t == nt - 2);
;             if constexpr (RS) { if (t == 16 || t == 32) { const PG8_LAS float* tp = rs_tab + (ui & 1) * 768 + (t == 32 ? 256 : 0);
;                 _Pragma("unroll") for (int a = 0; a < 2; ++a) _Pragma("unroll") for (int m = 0; m < 4; ++m) { const float f = tp[a * HALF + wr * 64 + m * 16 + fr];
;                     _Pragma("unroll") for (int b = 0; b < 2; ++b) _Pragma("unroll") for (int n = 0; n < 2; ++n) acc[a][b][m][n] = acc[a][b][m][n] * f; } } }
;             const char* a1 = cA + (size_t)(t + 1) * kstep;
;             const char* a2 = last ? nA : cA + (size_t)(t + 2) * kstep; const char* b2 = last ? nB : cB + (size_t)(t + 2) * kstep;
;             const char* a3 = a2 + kstep; const char* b3 = b2 + kstep;
;             if (last && has_next) S.a_ready(nxt);
;             if constexpr (SP2) {
;             PG8_LDB(B0, 0, 0); PG8_LDB(B1, 0, 1); PG8_SCHED; PG8_LDA(At, 0, 0); PG8_STAGE(PG8_SA(1, 1), a1 + hstep, voffA);
;             PG8_WAIT_V(8); PG8_WAIT_L(0); PG8_BAR; PG8_MMA(0, 0, At, B0); PG8_MMA(0, 1, At, B1); PG8_BAR; PG8_SCHED;
;             PG8_LDA(At, 0, 1); PG8_STAGE(PG8_SB(0, 0), b2, voffB); PG8_STAGE(PG8_SB(0, 1), b2 + hstep, voffB); PG8_STAGE(PG8_SA(0, 0), a2, voffA);
;             PG8_WAIT_V(8); PG8_WAIT_L(0); PG8_BAR; PG8_MMA(1, 0, At, B0); PG8_MMA(1, 1, At, B1); PG8_BAR; PG8_SCHED;
.LBB0_195:
	s_ashr_i32 s19, s18, 31
	s_lshl_b64 s[20:21], s[18:19], 20
	s_add_u32 s20, s30, s20
	s_addc_u32 s21, s31, s21
	s_and_b64 s[44:45], s[6:7], exec
	s_cselect_b32 s5, s21, s57
	s_cselect_b32 s19, s20, s56
	s_ashr_i32 s17, s16, 31
	s_lshl_b64 s[44:45], s[16:17], 20
	s_add_u32 s44, s24, s44
	s_addc_u32 s45, s25, s45
	s_and_b64 s[60:61], s[6:7], exec
	s_cselect_b32 s17, s45, s59
	s_cselect_b32 s47, s44, s58
	s_add_u32 s56, s56, 0x84000
	s_addc_u32 s57, s57, 0
	s_add_u32 s87, s58, 0x8000
	s_addc_u32 s88, s59, 0
	s_mov_b32 s89, -2
	s_waitcnt lgkmcnt(0)
	ds_read_b128 v[130:133], v161
	ds_read_b128 v[134:137], v161 offset:1024
	ds_read_b128 v[152:155], v161 offset:2048
	ds_read_b128 v[156:159], v161 offset:3072
	s_add_u32 s58, s56, 0xfff84000
	s_addc_u32 s59, s57, -1
	s_cmp_eq_u32 s89, 28
	s_cselect_b32 s70, s19, s58
	ds_read_b128 v[166:169], v162
	ds_read_b128 v[170:173], v162 offset:1024
	ds_read_b128 v[174:177], v162 offset:2048
	ds_read_b128 v[182:185], v162 offset:3072
	s_cselect_b32 s71, s5, s59
	s_cselect_b32 s60, s47, s87
	s_cselect_b32 s61, s17, s88
	s_add_u32 s58, s70, 0x4000
	ds_read_b128 v[188:191], v163
	ds_read_b128 v[192:195], v163 offset:1024
	ds_read_b128 v[196:199], v163 offset:2048
	ds_read_b128 v[200:203], v163 offset:3072
	s_addc_u32 s59, s71, 0
	v_lshl_add_u64 v[178:179], s[56:57], 0, v[138:139]
	s_add_i32 m0, s72, 0xc000
	ds_read_b128 v[204:207], v163 offset:4096
	ds_read_b128 v[208:211], v163 offset:5120
	ds_read_b128 v[212:215], v163 offset:6144
	ds_read_b128 v[216:219], v163 offset:7168
	global_load_lds_dwordx4 v[178:179], off
	v_lshl_add_u64 v[178:179], s[56:57], 0, v[146:147]
	s_add_i32 m0, s72, 0xe000
	s_nop 0
	global_load_lds_dwordx4 v[178:179], off
	s_waitcnt vmcnt(8)
	s_waitcnt lgkmcnt(0)
	s_barrier
	s_setprio 1
	s_waitcnt lgkmcnt(0)
	v_mfma_f32_16x16x32_bf16 v[126:129], v[130:133], v[188:191], 0
	v_mfma_f32_16x16x32_bf16 v[126:129], v[134:137], v[192:195], v[126:129]
	v_mfma_f32_16x16x32_bf16 v[122:125], v[156:159], v[192:195], 0
	v_mfma_f32_16x16x32_bf16 v[122:125], v[152:155], v[188:191], v[122:125]
	v_mfma_f32_16x16x32_bf16 v[106:109], v[152:155], v[196:199], 0
	v_mfma_f32_16x16x32_bf16 v[106:109], v[156:159], v[200:203], v[106:109]
	v_mfma_f32_16x16x32_bf16 v[110:113], v[134:137], v[200:203], 0
	v_mfma_f32_16x16x32_bf16 v[110:113], v[130:133], v[196:199], v[110:113]
	v_mfma_f32_16x16x32_bf16 v[94:97], v[130:133], v[204:207], 0
	v_mfma_f32_16x16x32_bf16 v[94:97], v[134:137], v[208:211], v[94:97]
	v_mfma_f32_16x16x32_bf16 v[90:93], v[156:159], v[208:211], 0
	v_mfma_f32_16x16x32_bf16 v[90:93], v[152:155], v[204:207], v[90:93]
	v_mfma_f32_16x16x32_bf16 v[74:77], v[152:155], v[212:215], 0
	v_mfma_f32_16x16x32_bf16 v[74:77], v[156:159], v[216:219], v[74:77]
	v_mfma_f32_16x16x32_bf16 v[78:81], v[134:137], v[216:219], 0
	v_mfma_f32_16x16x32_bf16 v[78:81], v[130:133], v[212:215], v[78:81]
	s_setprio 0
	s_setprio 1
	v_mfma_f32_16x16x32_bf16 v[70:73], v[166:169], v[212:215], 0
	v_mfma_f32_16x16x32_bf16 v[70:73], v[170:173], v[216:219], v[70:73]
	v_mfma_f32_16x16x32_bf16 v[66:69], v[182:185], v[216:219], 0
	v_mfma_f32_16x16x32_bf16 v[66:69], v[174:177], v[212:215], v[66:69]
	v_mfma_f32_16x16x32_bf16 v[82:85], v[174:177], v[204:207], 0
	v_mfma_f32_16x16x32_bf16 v[82:85], v[182:185], v[208:211], v[82:85]
	v_mfma_f32_16x16x32_bf16 v[86:89], v[170:173], v[208:211], 0
	v_mfma_f32_16x16x32_bf16 v[86:89], v[166:169], v[204:207], v[86:89]
	v_mfma_f32_16x16x32_bf16 v[102:105], v[166:169], v[196:199], 0
	v_mfma_f32_16x16x32_bf16 v[102:105], v[170:173], v[200:203], v[102:105]
	v_mfma_f32_16x16x32_bf16 v[98:101], v[182:185], v[200:203], 0
	v_mfma_f32_16x16x32_bf16 v[98:101], v[174:177], v[196:199], v[98:101]
	v_mfma_f32_16x16x32_bf16 v[114:117], v[174:177], v[188:191], 0
	v_mfma_f32_16x16x32_bf16 v[114:117], v[182:185], v[192:195], v[114:117]
	v_mfma_f32_16x16x32_bf16 v[118:121], v[170:173], v[192:195], 0
	v_mfma_f32_16x16x32_bf16 v[118:121], v[166:169], v[188:191], v[118:121]
	s_setprio 0
	s_barrier
	ds_read_b128 v[188:191], v163 offset:16384
	ds_read_b128 v[192:195], v163 offset:17408
	ds_read_b128 v[196:199], v163 offset:18432
	ds_read_b128 v[200:203], v163 offset:19456
	s_add_i32 s90, s83, s15
	v_lshl_add_u64 v[178:179], s[60:61], 0, v[138:139]
	s_mov_b32 m0, s90
	s_nop 0
	global_load_lds_dwordx4 v[178:179], off
	s_add_i32 m0, s90, 0x2000
	s_add_u32 s90, s60, 0x80000
	v_lshl_add_u64 v[178:179], s[60:61], 0, v[140:141]
	s_addc_u32 s91, s61, 0
	s_add_i32 s92, s86, s15
	global_load_lds_dwordx4 v[178:179], off
	ds_read_b128 v[204:207], v163 offset:20480
	ds_read_b128 v[208:211], v163 offset:21504
	ds_read_b128 v[212:215], v163 offset:22528
	ds_read_b128 v[216:219], v163 offset:23552
	v_lshl_add_u64 v[178:179], s[90:91], 0, v[138:139]
	s_mov_b32 m0, s92
	s_nop 0
	global_load_lds_dwordx4 v[178:179], off
	v_lshl_add_u64 v[178:179], s[90:91], 0, v[140:141]
	s_add_i32 m0, s92, 0x2000
	s_nop 0
	global_load_lds_dwordx4 v[178:179], off
	v_lshl_add_u64 v[178:179], s[70:71], 0, v[138:139]
	s_mov_b32 m0, s72
	s_nop 0
	global_load_lds_dwordx4 v[178:179], off
	v_lshl_add_u64 v[178:179], s[70:71], 0, v[140:141]
	s_mov_b32 m0, s73
	s_nop 0
	global_load_lds_dwordx4 v[178:179], off
	s_waitcnt vmcnt(8)
	s_waitcnt lgkmcnt(0)
	s_barrier
; #define PG8_STAGE(bufoff, gbase, voff) do { _Pragma("unroll") for (int _i = 0; _i < 2; ++_i) \
;         __builtin_amdgcn_global_load_lds((const unsigned*)((const char*)(gbase) + (voff)[_i]), (PG8_LAS unsigned*)(lds + (bufoff) + ldsw + _i * 8192), 16, 0, 0); } while (0)
; #define PG8_LDA(dst, b, h) do { _Pragma("unroll") for (int m = 0; m < 4; ++m) _Pragma("unroll") for (int k = 0; k < 2; ++k) dst[m][k] = *(const PG8_LAS bf16x8*)(lds + PG8_SA(b, h) + aoff + m * 2048 + k * 1024); } while (0)
; #define PG8_LDB(dst, b, h) do { _Pragma("unroll") for (int n = 0; n < 2; ++n) _Pragma("unroll") for (int k = 0; k < 2; ++k) dst[n][k] = *(const PG8_LAS bf16x8*)(lds + PG8_SB(b, h) + boff + n * 2048 + k * 1024); } while (0)
; #define PG8_MMA(ai, bj, At, Bt) do { __builtin_amdgcn_s_setprio(1); _Pragma("unroll") for (int m = 0; m < 4; ++m) _Pragma("unroll") for (int n = 0; n < 2; ++n) _Pragma("unroll") for (int k = 0; k < 2; ++k) \
;         acc[ai][bj][m][n] = __builtin_amdgcn_mfma_f32_16x16x32_bf16(Bt[n][k], At[m][k], acc[ai][bj][m][n], 0, 0, 0); __builtin_amdgcn_s_setprio(0); } while (0)
; #define PG8_WAIT_V(n) asm volatile("s_waitcnt vmcnt(" #n ")" ::: "memory")
; #define PG8_WAIT_L(n) asm volatile("s_waitcnt lgkmcnt(" #n ")" ::: "memory")
; #define PG8_BAR __builtin_amdgcn_s_barrier()
; #define PG8_SCHED __builtin_amdgcn_sched_barrier(0)
; template <class Epi, class Sched, bool ALIGN_EPI = false, bool SP2 = false, bool RS = false, bool BPRE = false>
; __device__ __forceinline__ void gemm_phase(PG8_LAS unsigned char* lds, const Gemm g, const Sched& S, const Epi& E, const float* rs_ss = nullptr, PG8_LAS float* rs_tab = nullptr) {
;     ...
;             PG8_WAIT_V(8); PG8_WAIT_L(0); PG8_BAR; PG8_MMA(1, 0, At, B0); PG8_MMA(1, 1, At, B1); PG8_BAR; PG8_SCHED;
;             PG8_LDB(B0, 1, 0); PG8_LDB(B1, 1, 1); PG8_SCHED; PG8_LDA(At, 1, 0); PG8_STAGE(PG8_SA(0, 1), a2 + hstep, voffA);
;             PG8_WAIT_V(8); PG8_WAIT_L(0); PG8_BAR; PG8_MMA(0, 0, At, B0); PG8_MMA(0, 1, At, B1); PG8_BAR; PG8_SCHED;
	s_setprio 1
	s_waitcnt lgkmcnt(0)
	v_mfma_f32_16x16x32_bf16 v[62:65], v[130:133], v[188:191], 0
	v_mfma_f32_16x16x32_bf16 v[62:65], v[134:137], v[192:195], v[62:65]
	v_mfma_f32_16x16x32_bf16 v[58:61], v[156:159], v[192:195], 0
	v_mfma_f32_16x16x32_bf16 v[58:61], v[152:155], v[188:191], v[58:61]
	v_mfma_f32_16x16x32_bf16 v[42:45], v[152:155], v[196:199], 0
	v_mfma_f32_16x16x32_bf16 v[42:45], v[156:159], v[200:203], v[42:45]
	v_mfma_f32_16x16x32_bf16 v[46:49], v[134:137], v[200:203], 0
	v_mfma_f32_16x16x32_bf16 v[46:49], v[130:133], v[196:199], v[46:49]
	v_mfma_f32_16x16x32_bf16 v[30:33], v[130:133], v[204:207], 0
	v_mfma_f32_16x16x32_bf16 v[30:33], v[134:137], v[208:211], v[30:33]
	v_mfma_f32_16x16x32_bf16 v[26:29], v[156:159], v[208:211], 0
	v_mfma_f32_16x16x32_bf16 v[26:29], v[152:155], v[204:207], v[26:29]
	v_mfma_f32_16x16x32_bf16 v[10:13], v[152:155], v[212:215], 0
	v_mfma_f32_16x16x32_bf16 v[10:13], v[156:159], v[216:219], v[10:13]
	v_mfma_f32_16x16x32_bf16 v[14:17], v[134:137], v[216:219], 0
	v_mfma_f32_16x16x32_bf16 v[14:17], v[130:133], v[212:215], v[14:17]
	s_setprio 0
	s_setprio 1
	v_mfma_f32_16x16x32_bf16 v[6:9], v[166:169], v[212:215], 0
	v_mfma_f32_16x16x32_bf16 v[6:9], v[170:173], v[216:219], v[6:9]
	v_mfma_f32_16x16x32_bf16 v[2:5], v[182:185], v[216:219], 0
	v_mfma_f32_16x16x32_bf16 v[2:5], v[174:177], v[212:215], v[2:5]
	v_mfma_f32_16x16x32_bf16 v[18:21], v[174:177], v[204:207], 0
	v_mfma_f32_16x16x32_bf16 v[18:21], v[182:185], v[208:211], v[18:21]
	v_mfma_f32_16x16x32_bf16 v[22:25], v[170:173], v[208:211], 0
	v_mfma_f32_16x16x32_bf16 v[22:25], v[166:169], v[204:207], v[22:25]
	v_mfma_f32_16x16x32_bf16 v[38:41], v[166:169], v[196:199], 0
	v_mfma_f32_16x16x32_bf16 v[38:41], v[170:173], v[200:203], v[38:41]
	v_mfma_f32_16x16x32_bf16 v[34:37], v[182:185], v[200:203], 0
	v_mfma_f32_16x16x32_bf16 v[34:37], v[174:177], v[196:199], v[34:37]
	v_mfma_f32_16x16x32_bf16 v[50:53], v[174:177], v[188:191], 0
	v_mfma_f32_16x16x32_bf16 v[50:53], v[182:185], v[192:195], v[50:53]
	v_mfma_f32_16x16x32_bf16 v[54:57], v[170:173], v[192:195], 0
	v_mfma_f32_16x16x32_bf16 v[54:57], v[166:169], v[188:191], v[54:57]
	s_setprio 0
	s_barrier
	s_add_i32 s90, 0, 0x18000
	v_add_u32_e32 v143, s90, v160
	s_add_i32 s91, 0, 0x1c000
	ds_read_b128 v[130:133], v143
	ds_read_b128 v[134:137], v143 offset:1024
	ds_read_b128 v[152:155], v143 offset:2048
	ds_read_b128 v[156:159], v143 offset:3072
	s_add_u32 s70, s70, 0x80000
	v_add_u32_e32 v143, s91, v160
	ds_read_b128 v[166:169], v143
	ds_read_b128 v[170:173], v143 offset:1024
	ds_read_b128 v[174:177], v143 offset:2048
	ds_read_b128 v[182:185], v143 offset:3072
	s_addc_u32 s71, s71, 0
	s_mov_b32 m0, s74
	ds_read_b128 v[188:191], v163 offset:32768
	ds_read_b128 v[192:195], v163 offset:33792
	ds_read_b128 v[196:199], v163 offset:34816
	ds_read_b128 v[200:203], v163 offset:35840
	v_lshl_add_u64 v[178:179], s[70:71], 0, v[138:139]
	global_load_lds_dwordx4 v[178:179], off
	ds_read_b128 v[204:207], v163 offset:36864
	ds_read_b128 v[208:211], v163 offset:37888
	ds_read_b128 v[212:215], v163 offset:38912
	ds_read_b128 v[216:219], v163 offset:39936
	v_lshl_add_u64 v[178:179], s[70:71], 0, v[140:141]
	s_mov_b32 m0, s75
	s_nop 0
	global_load_lds_dwordx4 v[178:179], off
	s_waitcnt vmcnt(8)
	s_waitcnt lgkmcnt(0)
	s_barrier
	s_setprio 1
	s_waitcnt lgkmcnt(0)
	v_mfma_f32_16x16x32_bf16 v[126:129], v[130:133], v[188:191], v[126:129]
	v_mfma_f32_16x16x32_bf16 v[126:129], v[134:137], v[192:195], v[126:129]
	v_mfma_f32_16x16x32_bf16 v[122:125], v[156:159], v[192:195], v[122:125]
	v_mfma_f32_16x16x32_bf16 v[122:125], v[152:155], v[188:191], v[122:125]
	v_mfma_f32_16x16x32_bf16 v[106:109], v[152:155], v[196:199], v[106:109]
	v_mfma_f32_16x16x32_bf16 v[106:109], v[156:159], v[200:203], v[106:109]
	v_mfma_f32_16x16x32_bf16 v[110:113], v[134:137], v[200:203], v[110:113]
	v_mfma_f32_16x16x32_bf16 v[110:113], v[130:133], v[196:199], v[110:113]
	v_mfma_f32_16x16x32_bf16 v[94:97], v[130:133], v[204:207], v[94:97]
	v_mfma_f32_16x16x32_bf16 v[94:97], v[134:137], v[208:211], v[94:97]
	v_mfma_f32_16x16x32_bf16 v[90:93], v[156:159], v[208:211], v[90:93]
	v_mfma_f32_16x16x32_bf16 v[90:93], v[152:155], v[204:207], v[90:93]
	v_mfma_f32_16x16x32_bf16 v[74:77], v[152:155], v[212:215], v[74:77]
	v_mfma_f32_16x16x32_bf16 v[74:77], v[156:159], v[216:219], v[74:77]
	v_mfma_f32_16x16x32_bf16 v[78:81], v[134:137], v[216:219], v[78:81]
	v_mfma_f32_16x16x32_bf16 v[78:81], v[130:133], v[212:215], v[78:81]
	s_setprio 0
	s_setprio 1
	v_mfma_f32_16x16x32_bf16 v[70:73], v[166:169], v[212:215], v[70:73]
	v_mfma_f32_16x16x32_bf16 v[70:73], v[170:173], v[216:219], v[70:73]
	v_mfma_f32_16x16x32_bf16 v[66:69], v[182:185], v[216:219], v[66:69]
	v_mfma_f32_16x16x32_bf16 v[66:69], v[174:177], v[212:215], v[66:69]
	v_mfma_f32_16x16x32_bf16 v[82:85], v[174:177], v[204:207], v[82:85]
	v_mfma_f32_16x16x32_bf16 v[82:85], v[182:185], v[208:211], v[82:85]
	v_mfma_f32_16x16x32_bf16 v[86:89], v[170:173], v[208:211], v[86:89]
	v_mfma_f32_16x16x32_bf16 v[86:89], v[166:169], v[204:207], v[86:89]
	v_mfma_f32_16x16x32_bf16 v[102:105], v[166:169], v[196:199], v[102:105]
	v_mfma_f32_16x16x32_bf16 v[102:105], v[170:173], v[200:203], v[102:105]
	v_mfma_f32_16x16x32_bf16 v[98:101], v[182:185], v[200:203], v[98:101]
	v_mfma_f32_16x16x32_bf16 v[98:101], v[174:177], v[196:199], v[98:101]
	v_mfma_f32_16x16x32_bf16 v[114:117], v[174:177], v[188:191], v[114:117]
	v_mfma_f32_16x16x32_bf16 v[114:117], v[182:185], v[192:195], v[114:117]
	v_mfma_f32_16x16x32_bf16 v[118:121], v[170:173], v[192:195], v[118:121]
	v_mfma_f32_16x16x32_bf16 v[118:121], v[166:169], v[188:191], v[118:121]
	s_setprio 0
	s_barrier
; #define PG8_STAGE(bufoff, gbase, voff) do { _Pragma("unroll") for (int _i = 0; _i < 2; ++_i) \
;         __builtin_amdgcn_global_load_lds((const unsigned*)((const char*)(gbase) + (voff)[_i]), (PG8_LAS unsigned*)(lds + (bufoff) + ldsw + _i * 8192), 16, 0, 0); } while (0)
; #define PG8_LDA(dst, b, h) do { _Pragma("unroll") for (int m = 0; m < 4; ++m) _Pragma("unroll") for (int k = 0; k < 2; ++k) dst[m][k] = *(const PG8_LAS bf16x8*)(lds + PG8_SA(b, h) + aoff + m * 2048 + k * 1024); } while (0)
; #define PG8_LDB(dst, b, h) do { _Pragma("unroll") for (int n = 0; n < 2; ++n) _Pragma("unroll") for (int k = 0; k < 2; ++k) dst[n][k] = *(const PG8_LAS bf16x8*)(lds + PG8_SB(b, h) + boff + n * 2048 + k * 1024); } while (0)
; template <class Epi, class Sched, bool ALIGN_EPI = false, bool SP2 = false, bool RS = false, bool BPRE = false>
; __device__ __forceinline__ void gemm_phase(PG8_LAS unsigned char* lds, const Gemm g, const Sched& S, const Epi& E, const float* rs_ss = nullptr, PG8_LAS float* rs_tab = nullptr) {
;     ...
;             const char* a1 = cA + (size_t)(t + 1) * kstep;
;             const char* a2 = last ? nA : cA + (size_t)(t + 2) * kstep; const char* b2 = last ? nB : cB + (size_t)(t + 2) * kstep;
;             const char* a3 = a2 + kstep; const char* b3 = b2 + kstep;
;             if (last && has_next) S.a_ready(nxt);
;             if constexpr (SP2) {
;             PG8_LDB(B0, 0, 0); PG8_LDB(B1, 0, 1); PG8_SCHED; PG8_LDA(At, 0, 0); PG8_STAGE(PG8_SA(1, 1), a1 + hstep, voffA);
;             PG8_WAIT_V(8); PG8_WAIT_L(0); PG8_BAR; PG8_MMA(0, 0, At, B0); PG8_MMA(0, 1, At, B1); PG8_BAR; PG8_SCHED;
;             PG8_LDA(At, 0, 1); PG8_STAGE(PG8_SB(0, 0), b2, voffB); PG8_STAGE(PG8_SB(0, 1), b2 + hstep, voffB); PG8_STAGE(PG8_SA(0, 0), a2, voffA);
;             PG8_WAIT_V(8); PG8_WAIT_L(0); PG8_BAR; PG8_MMA(1, 0, At, B0); PG8_MMA(1, 1, At, B1); PG8_BAR; PG8_SCHED;
;             PG8_LDB(B0, 1, 0); PG8_LDB(B1, 1, 1); PG8_SCHED; PG8_LDA(At, 1, 0); PG8_STAGE(PG8_SA(0, 1), a2 + hstep, voffA);
;             PG8_WAIT_V(8); PG8_WAIT_L(0); PG8_BAR; PG8_MMA(0, 0, At, B0); PG8_MMA(0, 1, At, B1); PG8_BAR; PG8_SCHED;
;             PG8_LDA(At, 1, 1); PG8_STAGE(PG8_SB(1, 0), b3, voffB); PG8_STAGE(PG8_SB(1, 1), b3 + hstep, voffB); PG8_STAGE(PG8_SA(1, 0), a3, voffA);
;             PG8_WAIT_V(8); PG8_WAIT_L(0); PG8_BAR; PG8_MMA(1, 0, At, B0); PG8_MMA(1, 1, At, B1); PG8_BAR; PG8_SCHED;
	ds_read_b128 v[188:191], v163 offset:49152
	ds_read_b128 v[192:195], v163 offset:50176
	ds_read_b128 v[196:199], v163 offset:51200
	ds_read_b128 v[200:203], v163 offset:52224
	s_add_u32 s70, s60, 0x4000
	s_addc_u32 s71, s61, 0
	s_add_i32 s90, s90, s15
	v_lshl_add_u64 v[178:179], s[70:71], 0, v[138:139]
	s_mov_b32 m0, s90
	s_nop 0
	global_load_lds_dwordx4 v[178:179], off
	s_add_i32 m0, s90, 0x2000
	s_add_u32 s60, s60, 0x84000
	v_lshl_add_u64 v[178:179], s[70:71], 0, v[140:141]
	s_addc_u32 s61, s61, 0
	s_add_i32 s70, s91, s15
	ds_read_b128 v[204:207], v163 offset:53248
	ds_read_b128 v[208:211], v163 offset:54272
	ds_read_b128 v[212:215], v163 offset:55296
	ds_read_b128 v[216:219], v163 offset:56320
	global_load_lds_dwordx4 v[178:179], off
	v_lshl_add_u64 v[178:179], s[60:61], 0, v[138:139]
	s_mov_b32 m0, s70
	s_nop 0
	global_load_lds_dwordx4 v[178:179], off
	v_lshl_add_u64 v[178:179], s[60:61], 0, v[140:141]
	s_add_i32 m0, s70, 0x2000
	s_nop 0
	global_load_lds_dwordx4 v[178:179], off
	v_lshl_add_u64 v[178:179], s[58:59], 0, v[138:139]
	s_mov_b32 m0, s79
	s_nop 0
	global_load_lds_dwordx4 v[178:179], off
	v_lshl_add_u64 v[178:179], s[58:59], 0, v[140:141]
	s_mov_b32 m0, s80
	s_nop 0
	global_load_lds_dwordx4 v[178:179], off
	s_waitcnt vmcnt(8)
	s_waitcnt lgkmcnt(0)
	s_barrier
	s_setprio 1
	s_waitcnt lgkmcnt(0)
	v_mfma_f32_16x16x32_bf16 v[62:65], v[130:133], v[188:191], v[62:65]
	v_mfma_f32_16x16x32_bf16 v[62:65], v[134:137], v[192:195], v[62:65]
	v_mfma_f32_16x16x32_bf16 v[58:61], v[156:159], v[192:195], v[58:61]
	v_mfma_f32_16x16x32_bf16 v[58:61], v[152:155], v[188:191], v[58:61]
	v_mfma_f32_16x16x32_bf16 v[42:45], v[152:155], v[196:199], v[42:45]
	v_mfma_f32_16x16x32_bf16 v[42:45], v[156:159], v[200:203], v[42:45]
	v_mfma_f32_16x16x32_bf16 v[46:49], v[134:137], v[200:203], v[46:49]
	v_mfma_f32_16x16x32_bf16 v[46:49], v[130:133], v[196:199], v[46:49]
	v_mfma_f32_16x16x32_bf16 v[30:33], v[130:133], v[204:207], v[30:33]
	v_mfma_f32_16x16x32_bf16 v[30:33], v[134:137], v[208:211], v[30:33]
	v_mfma_f32_16x16x32_bf16 v[26:29], v[156:159], v[208:211], v[26:29]
	v_mfma_f32_16x16x32_bf16 v[26:29], v[152:155], v[204:207], v[26:29]
	v_mfma_f32_16x16x32_bf16 v[10:13], v[152:155], v[212:215], v[10:13]
	v_mfma_f32_16x16x32_bf16 v[10:13], v[156:159], v[216:219], v[10:13]
	v_mfma_f32_16x16x32_bf16 v[14:17], v[134:137], v[216:219], v[14:17]
	v_mfma_f32_16x16x32_bf16 v[14:17], v[130:133], v[212:215], v[14:17]
	s_setprio 0
	s_setprio 1
	v_mfma_f32_16x16x32_bf16 v[6:9], v[166:169], v[212:215], v[6:9]
	v_mfma_f32_16x16x32_bf16 v[6:9], v[170:173], v[216:219], v[6:9]
	v_mfma_f32_16x16x32_bf16 v[2:5], v[182:185], v[216:219], v[2:5]
	v_mfma_f32_16x16x32_bf16 v[2:5], v[174:177], v[212:215], v[2:5]
	v_mfma_f32_16x16x32_bf16 v[18:21], v[174:177], v[204:207], v[18:21]
	v_mfma_f32_16x16x32_bf16 v[18:21], v[182:185], v[208:211], v[18:21]
	v_mfma_f32_16x16x32_bf16 v[22:25], v[170:173], v[208:211], v[22:25]
	v_mfma_f32_16x16x32_bf16 v[22:25], v[166:169], v[204:207], v[22:25]
	v_mfma_f32_16x16x32_bf16 v[38:41], v[166:169], v[196:199], v[38:41]
	v_mfma_f32_16x16x32_bf16 v[38:41], v[170:173], v[200:203], v[38:41]
	v_mfma_f32_16x16x32_bf16 v[34:37], v[182:185], v[200:203], v[34:37]
	v_mfma_f32_16x16x32_bf16 v[34:37], v[174:177], v[196:199], v[34:37]
	v_mfma_f32_16x16x32_bf16 v[50:53], v[174:177], v[188:191], v[50:53]
	v_mfma_f32_16x16x32_bf16 v[50:53], v[182:185], v[192:195], v[50:53]
	v_mfma_f32_16x16x32_bf16 v[54:57], v[170:173], v[192:195], v[54:57]
	v_mfma_f32_16x16x32_bf16 v[54:57], v[166:169], v[188:191], v[54:57]
	s_setprio 0
	s_barrier
	s_add_i32 s89, s89, 2
	s_add_u32 s56, s56, 0x8000
	s_addc_u32 s57, s57, 0
	s_add_u32 s87, s87, 0x8000
	s_addc_u32 s88, s88, 0
.LBB0_196:
	ds_read_b128 v[130:133], v161
	ds_read_b128 v[134:137], v161 offset:1024
	ds_read_b128 v[152:155], v161 offset:2048
	ds_read_b128 v[156:159], v161 offset:3072
	s_add_u32 s58, s56, 0xfff84000
	s_addc_u32 s59, s57, -1
	s_cmp_eq_u32 s89, 28
	s_cselect_b32 s70, s19, s58
	ds_read_b128 v[166:169], v162
	ds_read_b128 v[170:173], v162 offset:1024
	ds_read_b128 v[174:177], v162 offset:2048
	ds_read_b128 v[182:185], v162 offset:3072
	s_cselect_b32 s71, s5, s59
	s_cselect_b32 s60, s47, s87
	s_cselect_b32 s61, s17, s88
	s_add_u32 s58, s70, 0x4000
	ds_read_b128 v[188:191], v163
	ds_read_b128 v[192:195], v163 offset:1024
	ds_read_b128 v[196:199], v163 offset:2048
	ds_read_b128 v[200:203], v163 offset:3072
	s_addc_u32 s59, s71, 0
	v_lshl_add_u64 v[178:179], s[56:57], 0, v[138:139]
	s_add_i32 m0, s72, 0xc000
	ds_read_b128 v[204:207], v163 offset:4096
	ds_read_b128 v[208:211], v163 offset:5120
	ds_read_b128 v[212:215], v163 offset:6144
	ds_read_b128 v[216:219], v163 offset:7168
	global_load_lds_dwordx4 v[178:179], off
	v_lshl_add_u64 v[178:179], s[56:57], 0, v[146:147]
	s_add_i32 m0, s72, 0xe000
	s_nop 0
	global_load_lds_dwordx4 v[178:179], off
	s_waitcnt vmcnt(8)
	s_waitcnt lgkmcnt(0)
	s_barrier
; #define PG8_STAGE(bufoff, gbase, voff) do { _Pragma("unroll") for (int _i = 0; _i < 2; ++_i) \
;         __builtin_amdgcn_global_load_lds((const unsigned*)((const char*)(gbase) + (voff)[_i]), (PG8_LAS unsigned*)(lds + (bufoff) + ldsw + _i * 8192), 16, 0, 0); } while (0)
; #define PG8_LDA(dst, b, h) do { _Pragma("unroll") for (int m = 0; m < 4; ++m) _Pragma("unroll") for (int k = 0; k < 2; ++k) dst[m][k] = *(const PG8_LAS bf16x8*)(lds + PG8_SA(b, h) + aoff + m * 2048 + k * 1024); } while (0)
; #define PG8_MMA(ai, bj, At, Bt) do { __builtin_amdgcn_s_setprio(1); _Pragma("unroll") for (int m = 0; m < 4; ++m) _Pragma("unroll") for (int n = 0; n < 2; ++n) _Pragma("unroll") for (int k = 0; k < 2; ++k) \
;         acc[ai][bj][m][n] = __builtin_amdgcn_mfma_f32_16x16x32_bf16(Bt[n][k], At[m][k], acc[ai][bj][m][n], 0, 0, 0); __builtin_amdgcn_s_setprio(0); } while (0)
; #define PG8_WAIT_V(n) asm volatile("s_waitcnt vmcnt(" #n ")" ::: "memory")
; #define PG8_WAIT_L(n) asm volatile("s_waitcnt lgkmcnt(" #n ")" ::: "memory")
; #define PG8_BAR __builtin_amdgcn_s_barrier()
; #define PG8_SCHED __builtin_amdgcn_sched_barrier(0)
; template <class Epi, class Sched, bool ALIGN_EPI = false, bool SP2 = false, bool RS = false, bool BPRE = false>
; __device__ __forceinline__ void gemm_phase(PG8_LAS unsigned char* lds, const Gemm g, const Sched& S, const Epi& E, const float* rs_ss = nullptr, PG8_LAS float* rs_tab = nullptr) {
;     ...
;             PG8_WAIT_V(8); PG8_WAIT_L(0); PG8_BAR; PG8_MMA(0, 0, At, B0); PG8_MMA(0, 1, At, B1); PG8_BAR; PG8_SCHED;
;             PG8_LDA(At, 0, 1); PG8_STAGE(PG8_SB(0, 0), b2, voffB); PG8_STAGE(PG8_SB(0, 1), b2 + hstep, voffB); PG8_STAGE(PG8_SA(0, 0), a2, voffA);
;             PG8_WAIT_V(8); PG8_WAIT_L(0); PG8_BAR; PG8_MMA(1, 0, At, B0); PG8_MMA(1, 1, At, B1); PG8_BAR; PG8_SCHED;
	s_setprio 1
	s_waitcnt lgkmcnt(0)
	v_mfma_f32_16x16x32_bf16 v[126:129], v[130:133], v[188:191], v[126:129]
	v_mfma_f32_16x16x32_bf16 v[126:129], v[134:137], v[192:195], v[126:129]
	v_mfma_f32_16x16x32_bf16 v[122:125], v[156:159], v[192:195], v[122:125]
	v_mfma_f32_16x16x32_bf16 v[122:125], v[152:155], v[188:191], v[122:125]
	v_mfma_f32_16x16x32_bf16 v[106:109], v[152:155], v[196:199], v[106:109]
	v_mfma_f32_16x16x32_bf16 v[106:109], v[156:159], v[200:203], v[106:109]
	v_mfma_f32_16x16x32_bf16 v[110:113], v[134:137], v[200:203], v[110:113]
	v_mfma_f32_16x16x32_bf16 v[110:113], v[130:133], v[196:199], v[110:113]
	v_mfma_f32_16x16x32_bf16 v[94:97], v[130:133], v[204:207], v[94:97]
	v_mfma_f32_16x16x32_bf16 v[94:97], v[134:137], v[208:211], v[94:97]
	v_mfma_f32_16x16x32_bf16 v[90:93], v[156:159], v[208:211], v[90:93]
	v_mfma_f32_16x16x32_bf16 v[90:93], v[152:155], v[204:207], v[90:93]
	v_mfma_f32_16x16x32_bf16 v[74:77], v[152:155], v[212:215], v[74:77]
	v_mfma_f32_16x16x32_bf16 v[74:77], v[156:159], v[216:219], v[74:77]
	v_mfma_f32_16x16x32_bf16 v[78:81], v[134:137], v[216:219], v[78:81]
	v_mfma_f32_16x16x32_bf16 v[78:81], v[130:133], v[212:215], v[78:81]
	s_setprio 0
	s_setprio 1
	v_mfma_f32_16x16x32_bf16 v[70:73], v[166:169], v[212:215], v[70:73]
	v_mfma_f32_16x16x32_bf16 v[70:73], v[170:173], v[216:219], v[70:73]
	v_mfma_f32_16x16x32_bf16 v[66:69], v[182:185], v[216:219], v[66:69]
	v_mfma_f32_16x16x32_bf16 v[66:69], v[174:177], v[212:215], v[66:69]
	v_mfma_f32_16x16x32_bf16 v[82:85], v[174:177], v[204:207], v[82:85]
	v_mfma_f32_16x16x32_bf16 v[82:85], v[182:185], v[208:211], v[82:85]
	v_mfma_f32_16x16x32_bf16 v[86:89], v[170:173], v[208:211], v[86:89]
	v_mfma_f32_16x16x32_bf16 v[86:89], v[166:169], v[204:207], v[86:89]
	v_mfma_f32_16x16x32_bf16 v[102:105], v[166:169], v[196:199], v[102:105]
	v_mfma_f32_16x16x32_bf16 v[102:105], v[170:173], v[200:203], v[102:105]
	v_mfma_f32_16x16x32_bf16 v[98:101], v[182:185], v[200:203], v[98:101]
	v_mfma_f32_16x16x32_bf16 v[98:101], v[174:177], v[196:199], v[98:101]
	v_mfma_f32_16x16x32_bf16 v[114:117], v[174:177], v[188:191], v[114:117]
	v_mfma_f32_16x16x32_bf16 v[114:117], v[182:185], v[192:195], v[114:117]
	v_mfma_f32_16x16x32_bf16 v[118:121], v[170:173], v[192:195], v[118:121]
	v_mfma_f32_16x16x32_bf16 v[118:121], v[166:169], v[188:191], v[118:121]
	s_setprio 0
	s_barrier
	ds_read_b128 v[188:191], v163 offset:16384
	ds_read_b128 v[192:195], v163 offset:17408
	ds_read_b128 v[196:199], v163 offset:18432
	ds_read_b128 v[200:203], v163 offset:19456
	s_add_i32 s90, s83, s15
	v_lshl_add_u64 v[178:179], s[60:61], 0, v[138:139]
	s_mov_b32 m0, s90
	s_nop 0
	global_load_lds_dwordx4 v[178:179], off
	s_add_i32 m0, s90, 0x2000
	s_add_u32 s90, s60, 0x80000
	v_lshl_add_u64 v[178:179], s[60:61], 0, v[140:141]
	s_addc_u32 s91, s61, 0
	s_add_i32 s92, s86, s15
	global_load_lds_dwordx4 v[178:179], off
	ds_read_b128 v[204:207], v163 offset:20480
	ds_read_b128 v[208:211], v163 offset:21504
	ds_read_b128 v[212:215], v163 offset:22528
	ds_read_b128 v[216:219], v163 offset:23552
	v_lshl_add_u64 v[178:179], s[90:91], 0, v[138:139]
	s_mov_b32 m0, s92
	s_nop 0
	global_load_lds_dwordx4 v[178:179], off
	v_lshl_add_u64 v[178:179], s[90:91], 0, v[140:141]
	s_add_i32 m0, s92, 0x2000
	s_nop 0
	global_load_lds_dwordx4 v[178:179], off
	v_lshl_add_u64 v[178:179], s[70:71], 0, v[138:139]
	s_mov_b32 m0, s72
	s_nop 0
	global_load_lds_dwordx4 v[178:179], off
	v_lshl_add_u64 v[178:179], s[70:71], 0, v[140:141]
	s_mov_b32 m0, s73
	s_nop 0
	global_load_lds_dwordx4 v[178:179], off
	s_waitcnt vmcnt(8)
	s_waitcnt lgkmcnt(0)
	s_barrier
	s_setprio 1
	s_waitcnt lgkmcnt(0)
	v_mfma_f32_16x16x32_bf16 v[62:65], v[130:133], v[188:191], v[62:65]
	v_mfma_f32_16x16x32_bf16 v[62:65], v[134:137], v[192:195], v[62:65]
	v_mfma_f32_16x16x32_bf16 v[58:61], v[156:159], v[192:195], v[58:61]
	v_mfma_f32_16x16x32_bf16 v[58:61], v[152:155], v[188:191], v[58:61]
	v_mfma_f32_16x16x32_bf16 v[42:45], v[152:155], v[196:199], v[42:45]
	v_mfma_f32_16x16x32_bf16 v[42:45], v[156:159], v[200:203], v[42:45]
	v_mfma_f32_16x16x32_bf16 v[46:49], v[134:137], v[200:203], v[46:49]
	v_mfma_f32_16x16x32_bf16 v[46:49], v[130:133], v[196:199], v[46:49]
	v_mfma_f32_16x16x32_bf16 v[30:33], v[130:133], v[204:207], v[30:33]
	v_mfma_f32_16x16x32_bf16 v[30:33], v[134:137], v[208:211], v[30:33]
	v_mfma_f32_16x16x32_bf16 v[26:29], v[156:159], v[208:211], v[26:29]
	v_mfma_f32_16x16x32_bf16 v[26:29], v[152:155], v[204:207], v[26:29]
	v_mfma_f32_16x16x32_bf16 v[10:13], v[152:155], v[212:215], v[10:13]
	v_mfma_f32_16x16x32_bf16 v[10:13], v[156:159], v[216:219], v[10:13]
	v_mfma_f32_16x16x32_bf16 v[14:17], v[134:137], v[216:219], v[14:17]
	v_mfma_f32_16x16x32_bf16 v[14:17], v[130:133], v[212:215], v[14:17]
	s_setprio 0
	s_setprio 1
	v_mfma_f32_16x16x32_bf16 v[6:9], v[166:169], v[212:215], v[6:9]
	v_mfma_f32_16x16x32_bf16 v[6:9], v[170:173], v[216:219], v[6:9]
	v_mfma_f32_16x16x32_bf16 v[2:5], v[182:185], v[216:219], v[2:5]
	v_mfma_f32_16x16x32_bf16 v[2:5], v[174:177], v[212:215], v[2:5]
	v_mfma_f32_16x16x32_bf16 v[18:21], v[174:177], v[204:207], v[18:21]
	v_mfma_f32_16x16x32_bf16 v[18:21], v[182:185], v[208:211], v[18:21]
	v_mfma_f32_16x16x32_bf16 v[22:25], v[170:173], v[208:211], v[22:25]
	v_mfma_f32_16x16x32_bf16 v[22:25], v[166:169], v[204:207], v[22:25]
	v_mfma_f32_16x16x32_bf16 v[38:41], v[166:169], v[196:199], v[38:41]
	v_mfma_f32_16x16x32_bf16 v[38:41], v[170:173], v[200:203], v[38:41]
	v_mfma_f32_16x16x32_bf16 v[34:37], v[182:185], v[200:203], v[34:37]
	v_mfma_f32_16x16x32_bf16 v[34:37], v[174:177], v[196:199], v[34:37]
	v_mfma_f32_16x16x32_bf16 v[50:53], v[174:177], v[188:191], v[50:53]
	v_mfma_f32_16x16x32_bf16 v[50:53], v[182:185], v[192:195], v[50:53]
	v_mfma_f32_16x16x32_bf16 v[54:57], v[170:173], v[192:195], v[54:57]
	v_mfma_f32_16x16x32_bf16 v[54:57], v[166:169], v[188:191], v[54:57]
	s_setprio 0
	s_barrier
; #define PG8_STAGE(bufoff, gbase, voff) do { _Pragma("unroll") for (int _i = 0; _i < 2; ++_i) \
;         __builtin_amdgcn_global_load_lds((const unsigned*)((const char*)(gbase) + (voff)[_i]), (PG8_LAS unsigned*)(lds + (bufoff) + ldsw + _i * 8192), 16, 0, 0); } while (0)
; #define PG8_LDA(dst, b, h) do { _Pragma("unroll") for (int m = 0; m < 4; ++m) _Pragma("unroll") for (int k = 0; k < 2; ++k) dst[m][k] = *(const PG8_LAS bf16x8*)(lds + PG8_SA(b, h) + aoff + m * 2048 + k * 1024); } while (0)
; #define PG8_LDB(dst, b, h) do { _Pragma("unroll") for (int n = 0; n < 2; ++n) _Pragma("unroll") for (int k = 0; k < 2; ++k) dst[n][k] = *(const PG8_LAS bf16x8*)(lds + PG8_SB(b, h) + boff + n * 2048 + k * 1024); } while (0)
; #define PG8_MMA(ai, bj, At, Bt) do { __builtin_amdgcn_s_setprio(1); _Pragma("unroll") for (int m = 0; m < 4; ++m) _Pragma("unroll") for (int n = 0; n < 2; ++n) _Pragma("unroll") for (int k = 0; k < 2; ++k) \
;         acc[ai][bj][m][n] = __builtin_amdgcn_mfma_f32_16x16x32_bf16(Bt[n][k], At[m][k], acc[ai][bj][m][n], 0, 0, 0); __builtin_amdgcn_s_setprio(0); } while (0)
; #define PG8_WAIT_V(n) asm volatile("s_waitcnt vmcnt(" #n ")" ::: "memory")
; #define PG8_WAIT_L(n) asm volatile("s_waitcnt lgkmcnt(" #n ")" ::: "memory")
; #define PG8_BAR __builtin_amdgcn_s_barrier()
; #define PG8_SCHED __builtin_amdgcn_sched_barrier(0)
; template <class Epi, class Sched, bool ALIGN_EPI = false, bool SP2 = false, bool RS = false, bool BPRE = false>
; __device__ __forceinline__ void gemm_phase(PG8_LAS unsigned char* lds, const Gemm g, const Sched& S, const Epi& E, const float* rs_ss = nullptr, PG8_LAS float* rs_tab = nullptr) {
;     ...
;             PG8_LDB(B0, 1, 0); PG8_LDB(B1, 1, 1); PG8_SCHED; PG8_LDA(At, 1, 0); PG8_STAGE(PG8_SA(0, 1), a2 + hstep, voffA);
;             PG8_WAIT_V(8); PG8_WAIT_L(0); PG8_BAR; PG8_MMA(0, 0, At, B0); PG8_MMA(0, 1, At, B1); PG8_BAR; PG8_SCHED;
	s_add_i32 s90, 0, 0x18000
	v_add_u32_e32 v143, s90, v160
	s_add_i32 s91, 0, 0x1c000
	ds_read_b128 v[130:133], v143
	ds_read_b128 v[134:137], v143 offset:1024
	ds_read_b128 v[152:155], v143 offset:2048
	ds_read_b128 v[156:159], v143 offset:3072
	s_add_u32 s70, s70, 0x80000
	v_add_u32_e32 v143, s91, v160
	ds_read_b128 v[166:169], v143
	ds_read_b128 v[170:173], v143 offset:1024
	ds_read_b128 v[174:177], v143 offset:2048
	ds_read_b128 v[182:185], v143 offset:3072
	s_addc_u32 s71, s71, 0
	s_mov_b32 m0, s74
	ds_read_b128 v[188:191], v163 offset:32768
	ds_read_b128 v[192:195], v163 offset:33792
	ds_read_b128 v[196:199], v163 offset:34816
	ds_read_b128 v[200:203], v163 offset:35840
	v_lshl_add_u64 v[178:179], s[70:71], 0, v[138:139]
	global_load_lds_dwordx4 v[178:179], off
	ds_read_b128 v[204:207], v163 offset:36864
	ds_read_b128 v[208:211], v163 offset:37888
	ds_read_b128 v[212:215], v163 offset:38912
	ds_read_b128 v[216:219], v163 offset:39936
	v_lshl_add_u64 v[178:179], s[70:71], 0, v[140:141]
	s_mov_b32 m0, s75
	s_nop 0
	global_load_lds_dwordx4 v[178:179], off
	s_waitcnt vmcnt(8)
	s_waitcnt lgkmcnt(0)
	s_barrier
	s_setprio 1
	s_waitcnt lgkmcnt(0)
	v_mfma_f32_16x16x32_bf16 v[126:129], v[130:133], v[188:191], v[126:129]
	v_mfma_f32_16x16x32_bf16 v[126:129], v[134:137], v[192:195], v[126:129]
	v_mfma_f32_16x16x32_bf16 v[122:125], v[156:159], v[192:195], v[122:125]
	v_mfma_f32_16x16x32_bf16 v[122:125], v[152:155], v[188:191], v[122:125]
	v_mfma_f32_16x16x32_bf16 v[106:109], v[152:155], v[196:199], v[106:109]
	v_mfma_f32_16x16x32_bf16 v[106:109], v[156:159], v[200:203], v[106:109]
	v_mfma_f32_16x16x32_bf16 v[110:113], v[134:137], v[200:203], v[110:113]
	v_mfma_f32_16x16x32_bf16 v[110:113], v[130:133], v[196:199], v[110:113]
	v_mfma_f32_16x16x32_bf16 v[94:97], v[130:133], v[204:207], v[94:97]
	v_mfma_f32_16x16x32_bf16 v[94:97], v[134:137], v[208:211], v[94:97]
	v_mfma_f32_16x16x32_bf16 v[90:93], v[156:159], v[208:211], v[90:93]
	v_mfma_f32_16x16x32_bf16 v[90:93], v[152:155], v[204:207], v[90:93]
	v_mfma_f32_16x16x32_bf16 v[74:77], v[152:155], v[212:215], v[74:77]
	v_mfma_f32_16x16x32_bf16 v[74:77], v[156:159], v[216:219], v[74:77]
	v_mfma_f32_16x16x32_bf16 v[78:81], v[134:137], v[216:219], v[78:81]
	v_mfma_f32_16x16x32_bf16 v[78:81], v[130:133], v[212:215], v[78:81]
	s_setprio 0
	s_setprio 1
	v_mfma_f32_16x16x32_bf16 v[70:73], v[166:169], v[212:215], v[70:73]
	v_mfma_f32_16x16x32_bf16 v[70:73], v[170:173], v[216:219], v[70:73]
	v_mfma_f32_16x16x32_bf16 v[66:69], v[182:185], v[216:219], v[66:69]
	v_mfma_f32_16x16x32_bf16 v[66:69], v[174:177], v[212:215], v[66:69]
	v_mfma_f32_16x16x32_bf16 v[82:85], v[174:177], v[204:207], v[82:85]
	v_mfma_f32_16x16x32_bf16 v[82:85], v[182:185], v[208:211], v[82:85]
	v_mfma_f32_16x16x32_bf16 v[86:89], v[170:173], v[208:211], v[86:89]
	v_mfma_f32_16x16x32_bf16 v[86:89], v[166:169], v[204:207], v[86:89]
	v_mfma_f32_16x16x32_bf16 v[102:105], v[166:169], v[196:199], v[102:105]
	v_mfma_f32_16x16x32_bf16 v[102:105], v[170:173], v[200:203], v[102:105]
	v_mfma_f32_16x16x32_bf16 v[98:101], v[182:185], v[200:203], v[98:101]
	v_mfma_f32_16x16x32_bf16 v[98:101], v[174:177], v[196:199], v[98:101]
	v_mfma_f32_16x16x32_bf16 v[114:117], v[174:177], v[188:191], v[114:117]
	v_mfma_f32_16x16x32_bf16 v[114:117], v[182:185], v[192:195], v[114:117]
	v_mfma_f32_16x16x32_bf16 v[118:121], v[170:173], v[192:195], v[118:121]
	v_mfma_f32_16x16x32_bf16 v[118:121], v[166:169], v[188:191], v[118:121]
	s_setprio 0
	s_barrier
; #define PG8_STAGE(bufoff, gbase, voff) do { _Pragma("unroll") for (int _i = 0; _i < 2; ++_i) \
;         __builtin_amdgcn_global_load_lds((const unsigned*)((const char*)(gbase) + (voff)[_i]), (PG8_LAS unsigned*)(lds + (bufoff) + ldsw + _i * 8192), 16, 0, 0); } while (0)
; #define PG8_LDA(dst, b, h) do { _Pragma("unroll") for (int m = 0; m < 4; ++m) _Pragma("unroll") for (int k = 0; k < 2; ++k) dst[m][k] = *(const PG8_LAS bf16x8*)(lds + PG8_SA(b, h) + aoff + m * 2048 + k * 1024); } while (0)
; #define PG8_MMA(ai, bj, At, Bt) do { __builtin_amdgcn_s_setprio(1); _Pragma("unroll") for (int m = 0; m < 4; ++m) _Pragma("unroll") for (int n = 0; n < 2; ++n) _Pragma("unroll") for (int k = 0; k < 2; ++k) \
;         acc[ai][bj][m][n] = __builtin_amdgcn_mfma_f32_16x16x32_bf16(Bt[n][k], At[m][k], acc[ai][bj][m][n], 0, 0, 0); __builtin_amdgcn_s_setprio(0); } while (0)
; #define PG8_WAIT_V(n) asm volatile("s_waitcnt vmcnt(" #n ")" ::: "memory")
; #define PG8_WAIT_L(n) asm volatile("s_waitcnt lgkmcnt(" #n ")" ::: "memory")
; #define PG8_BAR __builtin_amdgcn_s_barrier()
; #define PG8_SCHED __builtin_amdgcn_sched_barrier(0)
; template <class Epi, class Sched, bool ALIGN_EPI = false, bool SP2 = false, bool RS = false, bool BPRE = false>
; __device__ __forceinline__ void gemm_phase(PG8_LAS unsigned char* lds, const Gemm g, const Sched& S, const Epi& E, const float* rs_ss = nullptr, PG8_LAS float* rs_tab = nullptr) {
;     ...
;             PG8_LDA(At, 1, 1); PG8_STAGE(PG8_SB(1, 0), b3, voffB); PG8_STAGE(PG8_SB(1, 1), b3 + hstep, voffB); PG8_STAGE(PG8_SA(1, 0), a3, voffA);
;             PG8_WAIT_V(8); PG8_WAIT_L(0); PG8_BAR; PG8_MMA(1, 0, At, B0); PG8_MMA(1, 1, At, B1); PG8_BAR; PG8_SCHED;
;     ...
;         if constexpr (ALIGN_EPI) { if (wr == 0) PG8_BAR; }
	ds_read_b128 v[188:191], v163 offset:49152
	ds_read_b128 v[192:195], v163 offset:50176
	ds_read_b128 v[196:199], v163 offset:51200
	ds_read_b128 v[200:203], v163 offset:52224
	s_add_u32 s70, s60, 0x4000
	s_addc_u32 s71, s61, 0
	s_add_i32 s90, s90, s15
	v_lshl_add_u64 v[178:179], s[70:71], 0, v[138:139]
	s_mov_b32 m0, s90
	s_nop 0
	global_load_lds_dwordx4 v[178:179], off
	s_add_i32 m0, s90, 0x2000
	s_add_u32 s60, s60, 0x84000
	v_lshl_add_u64 v[178:179], s[70:71], 0, v[140:141]
	s_addc_u32 s61, s61, 0
	s_add_i32 s70, s91, s15
	ds_read_b128 v[204:207], v163 offset:53248
	ds_read_b128 v[208:211], v163 offset:54272
	ds_read_b128 v[212:215], v163 offset:55296
	ds_read_b128 v[216:219], v163 offset:56320
	global_load_lds_dwordx4 v[178:179], off
	v_lshl_add_u64 v[178:179], s[60:61], 0, v[138:139]
	s_mov_b32 m0, s70
	s_nop 0
	global_load_lds_dwordx4 v[178:179], off
	v_lshl_add_u64 v[178:179], s[60:61], 0, v[140:141]
	s_add_i32 m0, s70, 0x2000
	s_nop 0
	global_load_lds_dwordx4 v[178:179], off
	v_lshl_add_u64 v[178:179], s[58:59], 0, v[138:139]
	s_mov_b32 m0, s79
	s_nop 0
	global_load_lds_dwordx4 v[178:179], off
	v_lshl_add_u64 v[178:179], s[58:59], 0, v[140:141]
	s_mov_b32 m0, s80
	s_nop 0
	global_load_lds_dwordx4 v[178:179], off
	s_waitcnt vmcnt(8)
	s_waitcnt lgkmcnt(0)
	s_barrier
	s_setprio 1
	s_waitcnt lgkmcnt(0)
	v_mfma_f32_16x16x32_bf16 v[62:65], v[130:133], v[188:191], v[62:65]
	v_mfma_f32_16x16x32_bf16 v[62:65], v[134:137], v[192:195], v[62:65]
	v_mfma_f32_16x16x32_bf16 v[58:61], v[156:159], v[192:195], v[58:61]
	v_mfma_f32_16x16x32_bf16 v[58:61], v[152:155], v[188:191], v[58:61]
	v_mfma_f32_16x16x32_bf16 v[42:45], v[152:155], v[196:199], v[42:45]
	v_mfma_f32_16x16x32_bf16 v[42:45], v[156:159], v[200:203], v[42:45]
	v_mfma_f32_16x16x32_bf16 v[46:49], v[134:137], v[200:203], v[46:49]
	v_mfma_f32_16x16x32_bf16 v[46:49], v[130:133], v[196:199], v[46:49]
	v_mfma_f32_16x16x32_bf16 v[30:33], v[130:133], v[204:207], v[30:33]
	v_mfma_f32_16x16x32_bf16 v[30:33], v[134:137], v[208:211], v[30:33]
	v_mfma_f32_16x16x32_bf16 v[26:29], v[156:159], v[208:211], v[26:29]
	v_mfma_f32_16x16x32_bf16 v[26:29], v[152:155], v[204:207], v[26:29]
	v_mfma_f32_16x16x32_bf16 v[10:13], v[152:155], v[212:215], v[10:13]
	v_mfma_f32_16x16x32_bf16 v[10:13], v[156:159], v[216:219], v[10:13]
	v_mfma_f32_16x16x32_bf16 v[14:17], v[134:137], v[216:219], v[14:17]
	v_mfma_f32_16x16x32_bf16 v[14:17], v[130:133], v[212:215], v[14:17]
	s_setprio 0
	s_setprio 1
	v_mfma_f32_16x16x32_bf16 v[6:9], v[166:169], v[212:215], v[6:9]
	v_mfma_f32_16x16x32_bf16 v[6:9], v[170:173], v[216:219], v[6:9]
	v_mfma_f32_16x16x32_bf16 v[2:5], v[182:185], v[216:219], v[2:5]
	v_mfma_f32_16x16x32_bf16 v[2:5], v[174:177], v[212:215], v[2:5]
	v_mfma_f32_16x16x32_bf16 v[18:21], v[174:177], v[204:207], v[18:21]
	v_mfma_f32_16x16x32_bf16 v[18:21], v[182:185], v[208:211], v[18:21]
	v_mfma_f32_16x16x32_bf16 v[22:25], v[170:173], v[208:211], v[22:25]
	v_mfma_f32_16x16x32_bf16 v[22:25], v[166:169], v[204:207], v[22:25]
	v_mfma_f32_16x16x32_bf16 v[38:41], v[166:169], v[196:199], v[38:41]
	v_mfma_f32_16x16x32_bf16 v[38:41], v[170:173], v[200:203], v[38:41]
	v_mfma_f32_16x16x32_bf16 v[34:37], v[182:185], v[200:203], v[34:37]
	v_mfma_f32_16x16x32_bf16 v[34:37], v[174:177], v[196:199], v[34:37]
	v_mfma_f32_16x16x32_bf16 v[50:53], v[174:177], v[188:191], v[50:53]
	v_mfma_f32_16x16x32_bf16 v[50:53], v[182:185], v[192:195], v[50:53]
	v_mfma_f32_16x16x32_bf16 v[54:57], v[170:173], v[192:195], v[54:57]
	v_mfma_f32_16x16x32_bf16 v[54:57], v[166:169], v[188:191], v[54:57]
	s_setprio 0
	s_barrier
	s_add_i32 s89, s89, 2
	s_add_u32 s56, s56, 0x8000
	s_addc_u32 s57, s57, 0
	s_add_u32 s87, s87, 0x8000
	s_addc_u32 s88, s88, 0
	s_cmp_gt_u32 s89, 29
	s_cbranch_scc0 .LBB0_196
	s_and_b64 vcc, exec, s[12:13]
	s_cbranch_vccz .LBB0_199
	s_barrier
